# HGRN2 output chunks: state, gate and second value piece loaded at the top of the chunk with the other operand pieces (were issued behind barriers with exposed round trips)
# speedup vs baseline: 1.0121x; 1.0018x over previous
.LBB0_1032:
	s_mov_b64 s[0:1], s[58:59]
	s_load_dwordx2 s[10:11], s[0:1], 0x158
	s_mov_b64 s[0:1], s[58:59]
	s_mov_b64 s[12:13], s[58:59]
	s_load_dwordx2 s[16:17], s[0:1], 0x158
	s_waitcnt lgkmcnt(0)
	s_add_u32 s1, s10, 0x12f00000
	s_addc_u32 s22, s11, 0
	s_load_dwordx2 s[10:11], s[12:13], 0x90
	s_mov_b64 s[12:13], s[58:59]
	s_and_b32 s0, s8, 0xfffff800
	s_and_b32 s14, s20, 0x7c0
	s_load_dwordx2 s[12:13], s[12:13], 0x158
	v_mbcnt_lo_u32_b32 v25, -1, 0
	v_mbcnt_hi_u32_b32 v25, -1, v25
	s_or_b32 s14, s0, s14
	v_add_u32_e32 v40, s61, v25
	s_bfe_u32 s0, s56, 0x20005
	v_lshlrev_b32_e32 v11, 3, v40
	s_lshl_b32 s15, s0, 8
	v_and_b32_e32 v9, 0x78, v11
	s_add_u32 s18, s1, s15
	s_addc_u32 s19, s22, 0
	v_lshlrev_b32_e32 v156, 1, v9
	v_ashrrev_i32_e32 v24, 4, v40
	v_lshl_add_u64 v[0:1], s[18:19], 0, v[156:157]
	v_add_u32_e32 v2, s14, v24
	v_mad_i64_i32 v[4:5], s[18:19], v2, s83, v[0:1]
	v_add_co_u32_e32 v6, vcc, s72, v4
	v_add_u32_e32 v27, 0x200, v40
	s_nop 0
	v_addc_co_u32_e32 v7, vcc, 0, v5, vcc
	global_load_dwordx4 v[12:15], v[6:7], off
	v_ashrrev_i32_e32 v26, 4, v27
	s_lshl_b32 s15, s0, 9
	v_lshlrev_b32_e32 v2, 2, v9
	v_add_u32_e32 v3, s14, v26
	s_add_i32 s15, s15, 0
	v_add_u32_e32 v10, s43, v2
	v_mad_i64_i32 v[0:1], s[18:19], v3, s83, v[0:1]
	v_add_u32_e32 v2, s15, v2
	v_add_u32_e32 v50, 0x22400, v2
	v_add_co_u32_e32 v42, vcc, s72, v0
	ds_read_b128 v[16:19], v50
	s_nop 0
	v_addc_co_u32_e32 v43, vcc, 0, v1, vcc
	global_load_dwordx4 v[0:3], v[0:1], off offset:3072
	s_nop 0
	global_load_dwordx4 v[20:23], v[6:7], off offset:1024
	global_load_dwordx4 v[70:73], v[6:7], off offset:2048
	global_load_dwordx4 v[74:77], v[42:43], off offset:2048
	global_load_dwordx4 v[102:105], v[42:43], off offset:1024
	v_lshlrev_b32_e32 v78, 9, v24
	v_lshlrev_b32_e32 v79, 4, v40
	v_and_b32_e32 v79, 0xf0, v79
	v_or_b32_e32 v78, v78, v79
	v_mov_b32_e32 v79, 0
	v_lshl_add_u64 v[78:79], s[16:17], 0, v[78:79]
	v_lshl_add_u64 v[78:79], v[78:79], 0, s[4:5]
	v_mov_b32_e32 v80, 0x4000
	v_mov_b32_e32 v81, 0
	v_lshl_add_u64 v[80:81], v[78:79], 0, v[80:81]
	global_load_dwordx4 v[82:85], v[78:79], off
	global_load_dwordx4 v[86:89], v[78:79], off offset:256
	global_load_dwordx4 v[94:97], v[80:81], off
	global_load_dwordx4 v[98:101], v[80:81], off offset:256
	s_nop 0
	global_load_dwordx4 v[4:7], v[4:5], off offset:3072
	ds_read_b128 v[28:31], v50 offset:16
	global_load_dwordx4 v[32:35], v[42:43], off
	s_waitcnt lgkmcnt(0)
	v_mov_b32_e32 v37, v18
	v_mov_b32_e32 v18, v17
	v_mov_b32_e32 v36, v16
	v_mov_b32_e32 v16, v28
	v_pk_add_f32 v[44:45], v[18:19], 1.0 op_sel_hi:[1,0] neg_lo:[1,0] neg_hi:[1,0]
	v_pk_add_f32 v[38:39], v[36:37], 1.0 op_sel_hi:[1,0] neg_lo:[1,0] neg_hi:[1,0]
	v_mul_u32_u24_e32 v52, 0x90, v9
	s_waitcnt vmcnt(0)
	v_lshlrev_b32_e32 v8, 16, v12
	v_and_b32_e32 v12, 0xffff0000, v12
	v_lshlrev_b32_e32 v17, 16, v13
	v_and_b32_e32 v13, 0xffff0000, v13
	v_lshlrev_b32_e32 v28, 16, v14
	v_and_b32_e32 v14, 0xffff0000, v14
	v_lshlrev_b32_e32 v41, 16, v15
	v_and_b32_e32 v15, 0xffff0000, v15
	v_mul_f32_e32 v12, 0xbfb8aa3b, v12
	v_mul_f32_e32 v13, 0xbfb8aa3b, v13
	v_mul_f32_e32 v8, 0xbfb8aa3b, v8
	v_mul_f32_e32 v17, 0xbfb8aa3b, v17
	v_mul_f32_e32 v28, 0xbfb8aa3b, v28
	v_mul_f32_e32 v14, 0xbfb8aa3b, v14
	v_mul_f32_e32 v41, 0xbfb8aa3b, v41
	v_mul_f32_e32 v15, 0xbfb8aa3b, v15
	v_exp_f32_e32 v12, v12
	v_exp_f32_e32 v13, v13
	v_exp_f32_e32 v8, v8
	v_exp_f32_e32 v17, v17
	v_exp_f32_e32 v28, v28
	v_exp_f32_e32 v14, v14
	v_exp_f32_e32 v41, v41
	v_exp_f32_e32 v15, v15
	v_add_f32_e32 v46, 1.0, v12
	v_add_f32_e32 v47, 1.0, v13
	v_add_f32_e32 v8, 1.0, v8
	v_add_f32_e32 v17, 1.0, v17
	v_add_f32_e32 v28, 1.0, v28
	v_add_f32_e32 v48, 1.0, v14
	v_add_f32_e32 v41, 1.0, v41
	v_add_f32_e32 v49, 1.0, v15
	v_rcp_f32_e32 v14, v46
	v_rcp_f32_e32 v15, v47
	v_rcp_f32_e32 v12, v8
	v_rcp_f32_e32 v13, v17
	v_rcp_f32_e32 v46, v28
	v_rcp_f32_e32 v47, v41
	v_rcp_f32_e32 v48, v48
	v_rcp_f32_e32 v49, v49
	v_mov_b32_e32 v17, v30
	v_pk_fma_f32 v[14:15], v[14:15], v[44:45], v[18:19]
	v_pk_add_f32 v[18:19], v[16:17], 1.0 op_sel_hi:[1,0] neg_lo:[1,0] neg_hi:[1,0]
	v_mov_b32_e32 v30, v29
	v_pk_fma_f32 v[12:13], v[12:13], v[38:39], v[36:37]
	v_pk_fma_f32 v[16:17], v[46:47], v[18:19], v[16:17]
	v_pk_add_f32 v[18:19], v[30:31], 1.0 op_sel_hi:[1,0] neg_lo:[1,0] neg_hi:[1,0]
	v_log_f32_e32 v36, v12
	v_log_f32_e32 v37, v14
	v_log_f32_e32 v38, v13
	v_log_f32_e32 v39, v15
	v_pk_fma_f32 v[18:19], v[48:49], v[18:19], v[30:31]
	v_log_f32_e32 v44, v16
	v_log_f32_e32 v46, v17
	v_log_f32_e32 v47, v19
	v_log_f32_e32 v45, v18
	v_lshlrev_b32_e32 v8, 9, v24
	v_pk_mul_f32 v[30:31], v[38:39], s[70:71] op_sel_hi:[1,0]
	v_pk_mul_f32 v[28:29], v[36:37], s[70:71] op_sel_hi:[1,0]
	v_add_u32_e32 v41, v10, v8
	v_bitop3_b32 v8, v24, 56, v11 bitop3:0x48
	v_pk_mul_f32 v[38:39], v[46:47], s[70:71] op_sel_hi:[1,0]
	v_pk_mul_f32 v[36:37], v[44:45], s[70:71] op_sel_hi:[1,0]
	ds_write_b128 v41, v[28:31]
	ds_write_b128 v41, v[36:39] offset:16
	v_lshl_add_u32 v28, v8, 1, 0
	v_lshlrev_b32_e32 v8, 1, v24
	v_and_b32_e32 v29, 14, v8
	v_add3_u32 v28, v28, v29, v52
	ds_write_b16 v28, v20 offset:44032
	ds_write_b16_d16_hi v28, v20 offset:44176
	ds_write_b16 v28, v21 offset:44320
	ds_write_b16_d16_hi v28, v21 offset:44464
	ds_write_b16 v28, v22 offset:44608
	ds_write_b16_d16_hi v28, v22 offset:44752
	v_mov_b32_e32 v36, v102
	v_mov_b32_e32 v37, v103
	v_mov_b32_e32 v38, v104
	v_mov_b32_e32 v39, v105
	v_and_b32_e32 v21, 0xffff0000, v32
	v_lshlrev_b32_e32 v20, 16, v32
	v_lshlrev_b32_e32 v22, 16, v33
	v_mul_f32_e32 v21, 0xbfb8aa3b, v21
	ds_write_b16 v28, v23 offset:44896
	ds_write_b16_d16_hi v28, v23 offset:45040
	v_and_b32_e32 v23, 0xffff0000, v33
	v_mul_f32_e32 v20, 0xbfb8aa3b, v20
	v_exp_f32_e32 v21, v21
	v_mul_f32_e32 v22, 0xbfb8aa3b, v22
	v_exp_f32_e32 v20, v20
	v_exp_f32_e32 v32, v22
	v_mul_f32_e32 v22, 0xbfb8aa3b, v23
	v_exp_f32_e32 v23, v22
	ds_read_b128 v[28:31], v50
	ds_read_b128 v[42:45], v50 offset:16
	v_add_f32_e32 v21, 1.0, v21
	v_add_f32_e32 v20, 1.0, v20
	v_rcp_f32_e32 v22, v21
	v_add_f32_e32 v21, 1.0, v32
	v_rcp_f32_e32 v20, v20
	v_rcp_f32_e32 v21, v21
	v_add_f32_e32 v23, 1.0, v23
	v_rcp_f32_e32 v23, v23
	s_waitcnt lgkmcnt(1)
	v_mov_b32_e32 v32, v28
	v_mov_b32_e32 v33, v30
	v_lshlrev_b32_e32 v46, 16, v34
	v_and_b32_e32 v47, 0xffff0000, v34
	v_lshlrev_b32_e32 v48, 16, v35
	v_and_b32_e32 v49, 0xffff0000, v35
	v_pk_add_f32 v[34:35], v[32:33], 1.0 op_sel_hi:[1,0] neg_lo:[1,0] neg_hi:[1,0]
	v_mov_b32_e32 v30, v29
	v_pk_fma_f32 v[20:21], v[20:21], v[34:35], v[32:33]
	v_pk_add_f32 v[32:33], v[30:31], 1.0 op_sel_hi:[1,0] neg_lo:[1,0] neg_hi:[1,0]
	v_log_f32_e32 v28, v20
	v_pk_fma_f32 v[22:23], v[22:23], v[32:33], v[30:31]
	v_mul_f32_e32 v31, 0xbfb8aa3b, v47
	v_mul_f32_e32 v30, 0xbfb8aa3b, v46
	v_exp_f32_e32 v31, v31
	v_mul_f32_e32 v32, 0xbfb8aa3b, v48
	v_exp_f32_e32 v30, v30
	v_exp_f32_e32 v32, v32
	v_mul_f32_e32 v33, 0xbfb8aa3b, v49
	v_exp_f32_e32 v33, v33
	v_add_f32_e32 v31, 1.0, v31
	v_add_f32_e32 v30, 1.0, v30
	v_rcp_f32_e32 v46, v31
	v_add_f32_e32 v31, 1.0, v32
	v_rcp_f32_e32 v30, v30
	v_rcp_f32_e32 v31, v31
	v_add_f32_e32 v32, 1.0, v33
	v_rcp_f32_e32 v47, v32
	s_waitcnt lgkmcnt(0)
	v_mov_b32_e32 v32, v42
	v_mov_b32_e32 v33, v44
	v_pk_add_f32 v[48:49], v[32:33], 1.0 op_sel_hi:[1,0] neg_lo:[1,0] neg_hi:[1,0]
	v_mov_b32_e32 v44, v43
	v_pk_fma_f32 v[32:33], v[30:31], v[48:49], v[32:33]
	v_pk_add_f32 v[30:31], v[44:45], 1.0 op_sel_hi:[1,0] neg_lo:[1,0] neg_hi:[1,0]
	v_log_f32_e32 v29, v22
	v_pk_fma_f32 v[30:31], v[46:47], v[30:31], v[44:45]
	v_log_f32_e32 v42, v32
	v_log_f32_e32 v48, v33
	v_log_f32_e32 v49, v31
	v_log_f32_e32 v43, v30
	v_log_f32_e32 v34, v21
	v_log_f32_e32 v35, v23
	v_pk_mul_f32 v[44:45], v[28:29], s[70:71] op_sel_hi:[1,0]
	v_lshlrev_b32_e32 v28, 9, v26
	v_pk_mul_f32 v[50:51], v[48:49], s[70:71] op_sel_hi:[1,0]
	v_pk_mul_f32 v[48:49], v[42:43], s[70:71] op_sel_hi:[1,0]
	v_add_u32_e32 v42, v10, v28
	v_bitop3_b32 v10, v26, 56, v11 bitop3:0x48
	v_lshl_add_u32 v28, v10, 1, 0
	v_lshlrev_b32_e32 v10, 1, v26
	v_and_b32_e32 v29, 14, v10
	v_pk_mul_f32 v[46:47], v[34:35], s[70:71] op_sel_hi:[1,0]
	v_add3_u32 v28, v28, v29, v52
	ds_write_b128 v42, v[44:47]
	ds_write_b128 v42, v[48:51] offset:16
	s_waitcnt vmcnt(0)
	ds_write_b16 v28, v36 offset:44032
	ds_write_b16_d16_hi v28, v36 offset:44176
	ds_write_b16 v28, v37 offset:44320
	ds_write_b16_d16_hi v28, v37 offset:44464
	ds_write_b16 v28, v38 offset:44608
	ds_write_b16_d16_hi v28, v38 offset:44752
	ds_write_b16 v28, v39 offset:44896
	ds_write_b16_d16_hi v28, v39 offset:45040
	v_and_b32_e32 v29, 0x7f, v40
	v_ashrrev_i32_e32 v28, 7, v40
	v_lshlrev_b32_e32 v34, 13, v28
	v_lshlrev_b32_e32 v29, 2, v29
	v_add3_u32 v43, s43, v34, v29
	s_waitcnt lgkmcnt(0)
	s_barrier
	ds_read2st64_b32 v[34:35], v43 offset1:2
	ds_read2st64_b32 v[36:37], v43 offset0:4 offset1:6
	ds_read2st64_b32 v[38:39], v43 offset0:8 offset1:10
	v_mov_b32_e32 v44, 0
	v_add_u32_e32 v29, 0, v29
	s_waitcnt lgkmcnt(2)
	v_add_f32_e32 v45, 0, v34
	v_add_f32_e32 v47, v45, v35
	ds_read2st64_b32 v[34:35], v43 offset0:12 offset1:14
	s_waitcnt lgkmcnt(2)
	v_add_f32_e32 v46, v47, v36
	v_add_f32_e32 v49, v46, v37
	s_waitcnt lgkmcnt(1)
	v_add_f32_e32 v48, v49, v38
	ds_read2st64_b32 v[36:37], v43 offset0:16 offset1:18
	v_add_f32_e32 v52, v48, v39
	s_waitcnt lgkmcnt(1)
	v_add_f32_e32 v50, v52, v34
	v_add_f32_e32 v51, v50, v35
	ds_read2st64_b32 v[34:35], v43 offset0:20 offset1:22
	ds_read2st64_b32 v[38:39], v43 offset0:24 offset1:26
	s_waitcnt lgkmcnt(2)
	v_add_f32_e32 v53, v51, v36
	v_add_f32_e32 v54, v53, v37
	ds_read2st64_b32 v[36:37], v43 offset0:28 offset1:30
	s_waitcnt lgkmcnt(2)
	v_add_f32_e32 v59, v54, v34
	v_add_f32_e32 v60, v59, v35
	s_waitcnt lgkmcnt(1)
	v_add_f32_e32 v57, v60, v38
	v_add_f32_e32 v58, v57, v39
	s_waitcnt lgkmcnt(0)
	v_add_f32_e32 v55, v58, v36
	v_add_f32_e32 v56, v55, v37
	v_lshl_add_u32 v34, v40, 2, 0
	v_cmp_lt_i32_e32 vcc, 0, v28
	ds_write_b32 v34, v56 offset:62464
	s_waitcnt lgkmcnt(0)
	s_barrier
	s_and_saveexec_b64 s[18:19], vcc
	s_cbranch_execz .LBB0_1040
	ds_read_b32 v34, v29 offset:62464
	s_waitcnt lgkmcnt(0)
	v_add_f32_e32 v44, 0, v34
	s_or_b64 exec, exec, s[18:19]
	v_cmp_lt_i32_e32 vcc, 1, v28
	s_and_saveexec_b64 s[18:19], vcc
	s_cbranch_execnz .LBB0_1041

.LBB0_1038:
	s_or_b64 exec, exec, s[18:19]
	v_lshlrev_b32_e32 v4, 16, v4
	v_mul_f32_e32 v43, 0xbfb8aa3b, v4
	v_exp_f32_e32 v43, v43
	v_mul_f32_e32 v44, 0xbfb8aa3b, v38
	v_exp_f32_e32 v45, v44
	v_lshlrev_b32_e32 v5, 16, v5
	v_add_f32_e32 v43, 1.0, v43
	v_rcp_f32_e32 v44, v43
	v_add_f32_e32 v43, 1.0, v45
	v_mul_f32_e32 v45, 0xbfb8aa3b, v5
	v_exp_f32_e32 v45, v45
	v_mul_f32_e32 v46, 0xbfb8aa3b, v39
	v_exp_f32_e32 v47, v46
	v_rcp_f32_e32 v46, v43
	v_add_f32_e32 v43, 1.0, v45
	v_rcp_f32_e32 v45, v43
	v_add_f32_e32 v43, 1.0, v47
	v_lshlrev_b32_e32 v6, 16, v6
	v_rcp_f32_e32 v47, v43
	v_mul_f32_e32 v43, 0xbfb8aa3b, v6
	v_exp_f32_e32 v43, v43
	v_mul_f32_e32 v48, 0xbfb8aa3b, v36
	v_exp_f32_e32 v49, v48
	v_lshlrev_b32_e32 v7, 16, v7
	v_add_f32_e32 v43, 1.0, v43
	v_rcp_f32_e32 v48, v43
	v_add_f32_e32 v43, 1.0, v49
	v_mul_f32_e32 v49, 0xbfb8aa3b, v7
	v_exp_f32_e32 v49, v49
	v_mul_f32_e32 v50, 0xbfb8aa3b, v37
	v_exp_f32_e32 v51, v50
	v_rcp_f32_e32 v50, v43
	v_add_f32_e32 v43, 1.0, v49
	v_rcp_f32_e32 v49, v43
	v_add_f32_e32 v43, 1.0, v51
	v_lshlrev_b32_e32 v0, 16, v0
	v_rcp_f32_e32 v51, v43
	v_mul_f32_e32 v43, 0xbfb8aa3b, v0
	v_exp_f32_e32 v43, v43
	v_mul_f32_e32 v52, 0xbfb8aa3b, v34
	v_exp_f32_e32 v53, v52
	v_lshlrev_b32_e32 v1, 16, v1
	v_add_f32_e32 v43, 1.0, v43
	v_rcp_f32_e32 v52, v43
	v_add_f32_e32 v43, 1.0, v53
	v_mul_f32_e32 v53, 0xbfb8aa3b, v1
	v_exp_f32_e32 v53, v53
	v_mul_f32_e32 v54, 0xbfb8aa3b, v35
	v_exp_f32_e32 v55, v54
	v_rcp_f32_e32 v54, v43
	v_add_f32_e32 v43, 1.0, v53
	v_lshlrev_b32_e32 v56, 16, v2
	v_rcp_f32_e32 v53, v43
	v_add_f32_e32 v43, 1.0, v55
	v_mul_f32_e32 v2, 0xbfb8aa3b, v56
	v_rcp_f32_e32 v55, v43
	v_exp_f32_e32 v2, v2
	v_mul_f32_e32 v43, 0xbfb8aa3b, v28
	v_exp_f32_e32 v43, v43
	v_lshlrev_b32_e32 v57, 16, v3
	v_add_f32_e32 v2, 1.0, v2
	v_mul_f32_e32 v3, 0xbfb8aa3b, v57
	v_rcp_f32_e32 v58, v2
	v_add_f32_e32 v2, 1.0, v43
	v_exp_f32_e32 v3, v3
	v_mul_f32_e32 v43, 0xbfb8aa3b, v29
	v_exp_f32_e32 v43, v43
	v_rcp_f32_e32 v60, v2
	v_add_f32_e32 v2, 1.0, v3
	v_pk_mul_f32 v[36:37], v[50:51], v[36:37]
	v_pk_mul_f32 v[50:51], v[52:53], v[0:1]
	v_lshl_add_u32 v0, v9, 2, 0
	v_rcp_f32_e32 v59, v2
	v_add_f32_e32 v2, 1.0, v43
	v_add_u32_e32 v9, 0x1bc00, v0
	v_rcp_f32_e32 v61, v2
	v_pk_mul_f32 v[44:45], v[44:45], v[4:5]
	v_pk_mul_f32 v[48:49], v[48:49], v[6:7]
	ds_read_b128 v[0:3], v9
	ds_read_b128 v[4:7], v41
	v_pk_add_f32 v[62:63], v[12:13], 1.0 op_sel_hi:[1,0] neg_lo:[1,0] neg_hi:[1,0]
	v_pk_add_f32 v[64:65], v[14:15], 1.0 op_sel_hi:[1,0] neg_lo:[1,0] neg_hi:[1,0]
	v_pk_mul_f32 v[38:39], v[46:47], v[38:39]
	v_pk_add_f32 v[46:47], v[16:17], 1.0 op_sel_hi:[1,0] neg_lo:[1,0] neg_hi:[1,0]
	v_pk_add_f32 v[66:67], v[18:19], 1.0 op_sel_hi:[1,0] neg_lo:[1,0] neg_hi:[1,0]
	ds_read_b128 v[12:15], v9 offset:16
	ds_read_b128 v[16:19], v41 offset:16
	s_waitcnt lgkmcnt(2)
	v_sub_f32_e32 v1, v5, v1
	v_mul_f32_e32 v5, 0x3fb8aa3b, v1
	v_mul_f32_e32 v1, 0xbfb8aa3b, v1
	v_sub_f32_e32 v2, v6, v2
	v_pk_mul_f32 v[34:35], v[54:55], v[34:35]
	v_exp_f32_e32 v54, v1
	v_mul_f32_e32 v1, 0x3fb8aa3b, v2
	v_mul_f32_e32 v2, 0xbfb8aa3b, v2
	v_pk_add_f32 v[52:53], v[30:31], 1.0 op_sel_hi:[1,0] neg_lo:[1,0] neg_hi:[1,0]
	v_exp_f32_e32 v30, v5
	v_exp_f32_e32 v5, v2
	v_sub_f32_e32 v2, v7, v3
	v_mul_f32_e32 v3, 0x3fb8aa3b, v2
	v_exp_f32_e32 v31, v3
	v_mul_f32_e32 v2, 0xbfb8aa3b, v2
	s_waitcnt lgkmcnt(0)
	v_sub_f32_e32 v3, v16, v12
	v_exp_f32_e32 v55, v2
	v_mul_f32_e32 v2, 0x3fb8aa3b, v3
	v_mul_f32_e32 v3, 0xbfb8aa3b, v3
	v_exp_f32_e32 v6, v3
	v_sub_f32_e32 v3, v17, v13
	v_mul_f32_e32 v7, 0x3fb8aa3b, v3
	v_exp_f32_e32 v12, v7
	v_sub_f32_e32 v7, v18, v14
	v_sub_f32_e32 v14, v19, v15
	v_sub_f32_e32 v4, v4, v0
	v_mul_f32_e32 v13, 0x3fb8aa3b, v14
	v_mul_f32_e32 v0, 0x3fb8aa3b, v4
	v_mul_f32_e32 v3, 0xbfb8aa3b, v3
	v_exp_f32_e32 v13, v13
	v_exp_f32_e32 v0, v0
	v_exp_f32_e32 v1, v1
	v_exp_f32_e32 v16, v3
	v_mul_f32_e32 v3, 0x3fb8aa3b, v7
	v_exp_f32_e32 v2, v2
	v_exp_f32_e32 v3, v3
	v_mul_f32_e32 v14, 0xbfb8aa3b, v14
	v_pk_mul_f32 v[12:13], v[36:37], v[12:13]
	v_mul_f32_e32 v4, 0xbfb8aa3b, v4
	v_exp_f32_e32 v17, v14
	v_pk_mul_f32 v[0:1], v[44:45], v[0:1]
	v_pk_mul_f32 v[14:15], v[38:39], v[30:31]
	v_bfe_u32 v18, v13, 16, 1
	v_bfe_u32 v19, v12, 16, 1
	v_exp_f32_e32 v4, v4
	v_mul_f32_e32 v7, 0xbfb8aa3b, v7
	v_pk_mul_f32 v[2:3], v[48:49], v[2:3]
	v_bfe_u32 v30, v15, 16, 1
	v_bfe_u32 v31, v14, 16, 1
	v_add3_u32 v12, v12, v19, s54
	v_add3_u32 v13, v13, v18, s54
	v_bfe_u32 v18, v0, 16, 1
	v_bfe_u32 v19, v1, 16, 1
	v_exp_f32_e32 v7, v7
	v_add3_u32 v14, v14, v31, s54
	v_add3_u32 v15, v15, v30, s54
	v_bfe_u32 v30, v2, 16, 1
	v_bfe_u32 v31, v3, 16, 1
	v_add3_u32 v1, v1, v19, s54
	v_add3_u32 v0, v0, v18, s54
	v_add3_u32 v3, v3, v31, s54
	v_add3_u32 v2, v2, v30, s54
	v_lshrrev_b32_e32 v0, 16, v0
	v_lshrrev_b32_e32 v1, 16, v1
	v_lshrrev_b32_e32 v2, 16, v2
	v_lshrrev_b32_e32 v3, 16, v3
	v_and_or_b32 v1, v15, s33, v1
	v_and_or_b32 v0, v14, s33, v0
	v_pk_mul_f32 v[14:15], v[66:67], v[16:17]
	v_and_or_b32 v3, v13, s33, v3
	v_and_or_b32 v2, v12, s33, v2
	v_pk_mul_f32 v[4:5], v[62:63], v[4:5]
	v_pk_mul_f32 v[12:13], v[64:65], v[54:55]
	v_bfe_u32 v16, v15, 16, 1
	v_pk_mul_f32 v[6:7], v[46:47], v[6:7]
	v_bfe_u32 v17, v14, 16, 1
	v_bfe_u32 v18, v13, 16, 1
	v_bfe_u32 v19, v12, 16, 1
	v_add3_u32 v15, v15, v16, s54
	v_bfe_u32 v16, v4, 16, 1
	v_add3_u32 v12, v12, v19, s54
	v_add3_u32 v13, v13, v18, s54
	v_add3_u32 v14, v14, v17, s54
	v_bfe_u32 v17, v5, 16, 1
	v_bfe_u32 v18, v6, 16, 1
	v_bfe_u32 v19, v7, 16, 1
	v_add3_u32 v4, v4, v16, s54
	v_add_u32_e32 v68, 0, v156
	v_add3_u32 v7, v7, v19, s54
	v_add3_u32 v6, v6, v18, s54
	v_add3_u32 v5, v5, v17, s54
	v_lshrrev_b32_e32 v4, 16, v4
	v_mul_lo_u32 v30, v24, s29
	v_lshrrev_b32_e32 v5, 16, v5
	v_lshrrev_b32_e32 v6, 16, v6
	v_lshrrev_b32_e32 v7, 16, v7
	v_and_or_b32 v4, v12, s33, v4
	v_add_u32_e32 v12, v68, v30
	v_and_or_b32 v7, v15, s33, v7
	v_and_or_b32 v6, v14, s33, v6
	v_and_or_b32 v5, v13, s33, v5
	ds_write_b128 v12, v[0:3]
	ds_write_b128 v12, v[4:7] offset:17408
	ds_read_b128 v[0:3], v9
	ds_read_b128 v[4:7], v42
	ds_read_b128 v[12:15], v9 offset:16
	ds_read_b128 v[16:19], v42 offset:16
	v_pk_mul_f32 v[36:37], v[58:59], v[56:57]
	v_pk_mul_f32 v[28:29], v[60:61], v[28:29]
	v_pk_add_f32 v[22:23], v[22:23], 1.0 op_sel_hi:[1,0] neg_lo:[1,0] neg_hi:[1,0]
	s_waitcnt lgkmcnt(2)
	v_sub_f32_e32 v1, v5, v1
	v_mul_f32_e32 v5, 0x3fb8aa3b, v1
	v_mul_f32_e32 v1, 0xbfb8aa3b, v1
	v_sub_f32_e32 v2, v6, v2
	v_exp_f32_e32 v42, v1
	v_mul_f32_e32 v1, 0x3fb8aa3b, v2
	v_mul_f32_e32 v2, 0xbfb8aa3b, v2
	v_exp_f32_e32 v38, v5
	v_exp_f32_e32 v5, v2
	v_sub_f32_e32 v2, v7, v3
	v_mul_f32_e32 v3, 0x3fb8aa3b, v2
	v_exp_f32_e32 v39, v3
	v_mul_f32_e32 v2, 0xbfb8aa3b, v2
	s_waitcnt lgkmcnt(0)
	v_sub_f32_e32 v3, v16, v12
	v_exp_f32_e32 v43, v2
	v_mul_f32_e32 v2, 0x3fb8aa3b, v3
	v_mul_f32_e32 v3, 0xbfb8aa3b, v3
	v_exp_f32_e32 v6, v3
	v_sub_f32_e32 v3, v17, v13
	v_mul_f32_e32 v7, 0x3fb8aa3b, v3
	v_exp_f32_e32 v12, v7
	v_mul_f32_e32 v3, 0xbfb8aa3b, v3
	v_sub_f32_e32 v7, v18, v14
	v_sub_f32_e32 v9, v19, v15
	v_sub_f32_e32 v4, v4, v0
	v_exp_f32_e32 v16, v3
	v_mul_f32_e32 v3, 0x3fb8aa3b, v7
	v_mul_f32_e32 v13, 0x3fb8aa3b, v9
	v_mul_f32_e32 v0, 0x3fb8aa3b, v4
	v_exp_f32_e32 v2, v2
	v_exp_f32_e32 v3, v3
	v_exp_f32_e32 v13, v13
	v_exp_f32_e32 v0, v0
	v_exp_f32_e32 v1, v1
	v_pk_mul_f32 v[14:15], v[34:35], v[38:39]
	v_mul_f32_e32 v7, 0xbfb8aa3b, v7
	v_mul_f32_e32 v9, 0xbfb8aa3b, v9
	v_pk_mul_f32 v[2:3], v[36:37], v[2:3]
	v_pk_mul_f32 v[12:13], v[28:29], v[12:13]
	v_bfe_u32 v19, v15, 16, 1
	v_mul_f32_e32 v4, 0xbfb8aa3b, v4
	v_exp_f32_e32 v7, v7
	v_exp_f32_e32 v17, v9
	v_pk_mul_f32 v[0:1], v[50:51], v[0:1]
	v_bfe_u32 v9, v13, 16, 1
	v_bfe_u32 v18, v12, 16, 1
	v_add3_u32 v15, v15, v19, s54
	v_bfe_u32 v19, v2, 16, 1
	v_exp_f32_e32 v4, v4
	v_bfe_u32 v28, v14, 16, 1
	v_add3_u32 v12, v12, v18, s54
	v_add3_u32 v9, v13, v9, s54
	v_bfe_u32 v13, v0, 16, 1
	v_bfe_u32 v18, v1, 16, 1
	v_add3_u32 v2, v2, v19, s54
	v_add3_u32 v14, v14, v28, s54
	v_bfe_u32 v28, v3, 16, 1
	v_add3_u32 v1, v1, v18, s54
	v_add3_u32 v0, v0, v13, s54
	v_lshrrev_b32_e32 v2, 16, v2
	v_pk_add_f32 v[32:33], v[32:33], 1.0 op_sel_hi:[1,0] neg_lo:[1,0] neg_hi:[1,0]
	v_add3_u32 v3, v3, v28, s54
	v_lshrrev_b32_e32 v0, 16, v0
	v_lshrrev_b32_e32 v1, 16, v1
	v_and_or_b32 v2, v12, s33, v2
	v_pk_mul_f32 v[12:13], v[22:23], v[42:43]
	v_pk_add_f32 v[20:21], v[20:21], 1.0 op_sel_hi:[1,0] neg_lo:[1,0] neg_hi:[1,0]
	v_lshrrev_b32_e32 v3, 16, v3
	v_and_or_b32 v1, v15, s33, v1
	v_and_or_b32 v0, v14, s33, v0
	v_pk_mul_f32 v[6:7], v[32:33], v[6:7]
	v_pk_mul_f32 v[14:15], v[52:53], v[16:17]
	v_bfe_u32 v18, v12, 16, 1
	s_ashr_i32 s15, s14, 31
	s_mul_i32 s19, s14, 0x1e00
	v_and_or_b32 v3, v9, s33, v3
	v_pk_mul_f32 v[4:5], v[20:21], v[4:5]
	v_bfe_u32 v9, v15, 16, 1
	v_bfe_u32 v16, v14, 16, 1
	v_bfe_u32 v17, v13, 16, 1
	v_add3_u32 v12, v12, v18, s54
	v_bfe_u32 v18, v7, 16, 1
	s_mul_hi_i32 s18, s14, 0x1e00
	s_add_u32 s19, s1, s19
	v_add3_u32 v13, v13, v17, s54
	v_add3_u32 v14, v14, v16, s54
	v_add3_u32 v9, v15, v9, s54
	v_bfe_u32 v15, v4, 16, 1
	v_bfe_u32 v16, v5, 16, 1
	v_bfe_u32 v17, v6, 16, 1
	v_add3_u32 v7, v7, v18, s54
	s_addc_u32 s22, s22, s18
	s_lshl_b32 s1, s0, 1
	v_add3_u32 v6, v6, v17, s54
	v_add3_u32 v5, v5, v16, s54
	v_add3_u32 v4, v4, v15, s54
	v_lshrrev_b32_e32 v7, 16, v7
	v_mul_lo_u32 v31, v26, s29
	s_add_u32 s18, s19, s1
	v_lshrrev_b32_e32 v4, 16, v4
	v_lshrrev_b32_e32 v5, 16, v5
	v_lshrrev_b32_e32 v6, 16, v6
	v_and_or_b32 v7, v9, s33, v7
	v_add_u32_e32 v9, v68, v31
	s_addc_u32 s19, s22, 0
	v_and_or_b32 v6, v14, s33, v6
	v_and_or_b32 v5, v13, s33, v5
	v_and_or_b32 v4, v12, s33, v4
	ds_write_b128 v9, v[0:3]
	ds_write_b128 v9, v[4:7] offset:17408
	v_lshl_add_u64 v[0:1], s[18:19], 0, v[156:157]
	v_lshl_add_u64 v[0:1], v[0:1], 0, s[48:49]
	v_mad_i64_i32 v[2:3], s[18:19], v24, s83, v[0:1]
	s_waitcnt lgkmcnt(0)
	s_barrier
	v_mov_b32_e32 v12, v70
	v_mov_b32_e32 v13, v71
	v_mov_b32_e32 v14, v72
	v_mov_b32_e32 v15, v73
	v_mad_i64_i32 v[0:1], s[18:19], v26, s83, v[0:1]
	v_mov_b32_e32 v16, v74
	v_mov_b32_e32 v17, v75
	v_mov_b32_e32 v18, v76
	v_mov_b32_e32 v19, v77
	v_ashrrev_i32_e32 v9, 31, v8
	v_lshlrev_b32_e32 v2, 1, v11
	v_lshlrev_b64 v[0:1], 8, v[8:9]
	v_and_b32_e32 v2, 0xf0, v2
	v_or_b32_e32 v0, v0, v2
	v_lshl_add_u64 v[0:1], s[16:17], 0, v[0:1]
	v_lshl_add_u64 v[0:1], v[0:1], 0, s[4:5]
	v_mov_b32_e32 v20, v82
	v_mov_b32_e32 v21, v83
	v_mov_b32_e32 v22, v84
	v_mov_b32_e32 v23, v85
	v_mov_b32_e32 v34, v86
	v_mov_b32_e32 v35, v87
	v_mov_b32_e32 v36, v88
	v_mov_b32_e32 v37, v89
	v_ashrrev_i32_e32 v11, 31, v10
	v_lshlrev_b64 v[0:1], 8, v[10:11]
	v_or_b32_e32 v0, v0, v2
	v_lshl_add_u64 v[0:1], s[16:17], 0, v[0:1]
	v_lshl_add_u64 v[4:5], v[0:1], 0, s[4:5]
	v_mov_b32_e32 v0, v94
	v_mov_b32_e32 v1, v95
	v_mov_b32_e32 v2, v96
	v_mov_b32_e32 v3, v97
	s_nop 0
	v_mov_b32_e32 v4, v98
	v_mov_b32_e32 v5, v99
	v_mov_b32_e32 v6, v100
	v_mov_b32_e32 v7, v101
	v_lshlrev_b32_e32 v8, 4, v25
	v_and_b32_e32 v8, 0xf0, v8
	v_add_u32_e32 v8, s43, v8
	v_ashrrev_i32_e32 v10, 3, v40
	v_add_u32_e32 v9, v8, v30
	v_lshlrev_b32_e32 v11, 2, v10
	v_add_u32_e32 v8, v8, v31
	s_add_i32 s16, 0, 0x1fc00
	v_readfirstlane_b32 s18, v40
	v_and_b32_e32 v32, 15, v25
	s_bfe_u32 s17, s18, 0x10006
	s_lshl_b32 s19, s17, 6
	s_waitcnt vmcnt(5)
	ds_write_b128 v9, v[12:15]
	v_and_b32_e32 v12, -8, v11
	v_or_b32_e32 v11, 4, v11
	s_waitcnt vmcnt(4)
	ds_write_b128 v8, v[16:19]
	v_add_u32_e32 v12, s16, v12
	v_add_u32_e32 v11, s16, v11
	ds_read_b32 v12, v12
	ds_read_b32 v11, v11
	v_and_b32_e32 v8, 12, v25
	v_lshlrev_b32_e32 v9, 5, v25
	v_and_or_b32 v8, v9, s44, v8
	s_waitcnt vmcnt(3)
	v_lshlrev_b32_e32 v9, 16, v20
	s_waitcnt vmcnt(2)
	v_lshlrev_b32_e32 v14, 16, v34
	s_waitcnt lgkmcnt(1)
	v_mul_f32_e32 v9, v12, v9
	s_waitcnt lgkmcnt(0)
	v_mul_f32_e32 v14, v11, v14
	v_bfe_u32 v28, v9, 16, 1
	v_add3_u32 v9, v9, v28, s54
	v_bfe_u32 v28, v14, 16, 1
	v_lshrrev_b32_e32 v9, 16, v9
	v_add3_u32 v14, v14, v28, s54
	v_and_or_b32 v9, v14, s33, v9
	v_and_b32_e32 v14, 0xffff0000, v20
	v_and_b32_e32 v13, -8, v10
	v_and_b32_e32 v20, 0xffff0000, v34
	v_mul_f32_e32 v14, v12, v14
	v_bitop3_b32 v17, v8, v13, 40 bitop3:0x6c
	v_lshlrev_b32_e32 v10, 1, v10
	v_ashrrev_i32_e32 v18, 3, v27
	v_mul_f32_e32 v20, v11, v20
	v_bfe_u32 v28, v14, 16, 1
	v_mad_u32_u24 v15, v8, s29, 0
	v_lshlrev_b32_e32 v17, 1, v17
	v_and_b32_e32 v10, 12, v10
	v_lshlrev_b32_e32 v19, 2, v18
	v_add3_u32 v14, v14, v28, s54
	v_bfe_u32 v28, v20, 16, 1
	v_add3_u32 v17, v15, v17, v10
	v_and_b32_e32 v27, -8, v19
	v_or_b32_e32 v19, 4, v19
	v_lshrrev_b32_e32 v14, 16, v14
	v_add3_u32 v20, v20, v28, s54
	v_add_u32_e32 v27, s16, v27
	v_add_u32_e32 v19, s16, v19
	v_and_or_b32 v14, v20, s33, v14
	v_add_u32_e32 v17, 0xf400, v17
	ds_read_b32 v27, v27
	ds_read_b32 v19, v19
	ds_write2_b32 v17, v9, v14 offset1:68
	v_lshlrev_b32_e32 v9, 16, v21
	v_lshlrev_b32_e32 v14, 16, v35
	v_mul_f32_e32 v9, v12, v9
	v_mul_f32_e32 v14, v11, v14
	v_bfe_u32 v20, v9, 16, 1
	v_add3_u32 v9, v9, v20, s54
	v_bfe_u32 v20, v14, 16, 1
	v_lshrrev_b32_e32 v9, 16, v9
	v_add3_u32 v14, v14, v20, s54
	v_and_or_b32 v9, v14, s33, v9
	v_and_b32_e32 v14, 0xffff0000, v21
	v_and_b32_e32 v20, 0xffff0000, v35
	v_mul_f32_e32 v14, v12, v14
	v_mul_f32_e32 v20, v11, v20
	v_bfe_u32 v21, v14, 16, 1
	v_add3_u32 v14, v14, v21, s54
	v_bfe_u32 v21, v20, 16, 1
	v_lshrrev_b32_e32 v14, 16, v14
	v_add3_u32 v20, v20, v21, s54
	v_and_or_b32 v14, v20, s33, v14
	ds_write2_b32 v17, v9, v14 offset0:136 offset1:204
	v_lshlrev_b32_e32 v14, 16, v22
	v_lshlrev_b32_e32 v17, 16, v36
	v_mul_f32_e32 v14, v12, v14
	v_or_b32_e32 v9, 16, v8
	v_mul_f32_e32 v17, v11, v17
	v_bfe_u32 v28, v14, 16, 1
	v_bitop3_b32 v13, v9, v13, 56 bitop3:0x6c
	v_add3_u32 v14, v14, v28, s54
	v_bfe_u32 v28, v17, 16, 1
	v_mad_u32_u24 v20, v9, s29, 0
	v_lshlrev_b32_e32 v13, 1, v13
	v_lshrrev_b32_e32 v14, 16, v14
	v_add3_u32 v17, v17, v28, s54
	v_add3_u32 v21, v20, v13, v10
	v_and_or_b32 v14, v17, s33, v14
	v_add_u32_e32 v16, 0xf400, v15
	ds_write_b32 v21, v14 offset:62464
	v_and_b32_e32 v14, 0xffff0000, v22
	v_and_b32_e32 v17, 0xffff0000, v36
	v_add3_u32 v10, v16, v13, v10
	v_mul_f32_e32 v13, v12, v14
	v_mul_f32_e32 v14, v11, v17
	v_bfe_u32 v17, v13, 16, 1
	v_add3_u32 v13, v13, v17, s54
	v_bfe_u32 v17, v14, 16, 1
	v_lshrrev_b32_e32 v13, 16, v13
	v_add3_u32 v14, v14, v17, s54
	v_and_or_b32 v13, v14, s33, v13
	v_lshlrev_b32_e32 v14, 16, v23
	v_lshlrev_b32_e32 v17, 16, v37
	v_mul_f32_e32 v14, v12, v14
	v_mul_f32_e32 v17, v11, v17
	v_bfe_u32 v21, v14, 16, 1
	v_add3_u32 v14, v14, v21, s54
	v_bfe_u32 v21, v17, 16, 1
	v_lshrrev_b32_e32 v14, 16, v14
	v_add3_u32 v17, v17, v21, s54
	v_and_or_b32 v14, v17, s33, v14
	v_add_u32_e32 v17, 0x1000, v10
	ds_write2_b32 v17, v13, v14 offset0:132 offset1:200
	v_and_b32_e32 v13, 0xffff0000, v23
	v_and_b32_e32 v14, 0xffff0000, v37
	v_mul_f32_e32 v12, v12, v13
	v_mul_f32_e32 v11, v11, v14
	v_bfe_u32 v13, v12, 16, 1
	v_add3_u32 v12, v12, v13, s54
	v_bfe_u32 v13, v11, 16, 1
	v_lshrrev_b32_e32 v12, 16, v12
	v_add3_u32 v11, v11, v13, s54
	v_and_or_b32 v11, v11, s33, v12
	ds_write_b32 v10, v11 offset:5168
	s_waitcnt vmcnt(1)
	v_lshlrev_b32_e32 v11, 16, v0
	s_waitcnt vmcnt(0)
	v_lshlrev_b32_e32 v12, 16, v4
	s_waitcnt lgkmcnt(6)
	v_mul_f32_e32 v11, v27, v11
	s_waitcnt lgkmcnt(5)
	v_mul_f32_e32 v12, v19, v12
	v_bfe_u32 v14, v11, 16, 1
	v_add3_u32 v11, v11, v14, s54
	v_bfe_u32 v14, v12, 16, 1
	v_and_b32_e32 v0, 0xffff0000, v0
	v_and_b32_e32 v10, -8, v18
	v_lshrrev_b32_e32 v11, 16, v11
	v_add3_u32 v12, v12, v14, s54
	v_and_b32_e32 v4, 0xffff0000, v4
	v_mul_f32_e32 v0, v27, v0
	v_bitop3_b32 v8, v8, v10, 40 bitop3:0x6c
	v_lshlrev_b32_e32 v13, 1, v18
	v_and_or_b32 v11, v12, s33, v11
	v_mul_f32_e32 v4, v19, v4
	v_bfe_u32 v12, v0, 16, 1
	v_lshlrev_b32_e32 v8, 1, v8
	v_and_b32_e32 v13, 12, v13
	v_add3_u32 v0, v0, v12, s54
	v_bfe_u32 v12, v4, 16, 1
	v_add3_u32 v8, v15, v8, v13
	v_lshrrev_b32_e32 v0, 16, v0
	v_add3_u32 v4, v4, v12, s54
	v_and_or_b32 v0, v4, s33, v0
	v_add_u32_e32 v4, 0xf400, v8
	ds_write2_b32 v4, v11, v0 offset1:68
	v_lshlrev_b32_e32 v0, 16, v1
	v_lshlrev_b32_e32 v8, 16, v5
	v_mul_f32_e32 v0, v27, v0
	v_mul_f32_e32 v8, v19, v8
	v_bfe_u32 v11, v0, 16, 1
	v_add3_u32 v0, v0, v11, s54
	v_bfe_u32 v11, v8, 16, 1
	v_and_b32_e32 v1, 0xffff0000, v1
	v_lshrrev_b32_e32 v0, 16, v0
	v_add3_u32 v8, v8, v11, s54
	v_and_b32_e32 v5, 0xffff0000, v5
	v_mul_f32_e32 v1, v27, v1
	v_and_or_b32 v0, v8, s33, v0
	v_mul_f32_e32 v5, v19, v5
	v_bfe_u32 v8, v1, 16, 1
	v_add3_u32 v1, v1, v8, s54
	v_bfe_u32 v8, v5, 16, 1
	v_lshrrev_b32_e32 v1, 16, v1
	v_add3_u32 v5, v5, v8, s54
	v_and_or_b32 v1, v5, s33, v1
	ds_write2_b32 v4, v0, v1 offset0:136 offset1:204
	v_lshlrev_b32_e32 v0, 16, v2
	v_lshlrev_b32_e32 v1, 16, v6
	v_mul_f32_e32 v0, v27, v0
	v_mul_f32_e32 v1, v19, v1
	v_bfe_u32 v8, v0, 16, 1
	v_bitop3_b32 v4, v9, v10, 56 bitop3:0x6c
	v_add3_u32 v0, v0, v8, s54
	v_bfe_u32 v8, v1, 16, 1
	v_lshlrev_b32_e32 v4, 1, v4
	v_lshrrev_b32_e32 v0, 16, v0
	v_add3_u32 v1, v1, v8, s54
	v_add3_u32 v5, v20, v4, v13
	v_and_or_b32 v0, v1, s33, v0
	ds_write_b32 v5, v0 offset:62464
	v_and_b32_e32 v0, 0xffff0000, v2
	v_and_b32_e32 v1, 0xffff0000, v6
	v_mul_f32_e32 v0, v27, v0
	v_add3_u32 v2, v16, v4, v13
	v_mul_f32_e32 v1, v19, v1
	v_bfe_u32 v4, v0, 16, 1
	v_add3_u32 v0, v0, v4, s54
	v_bfe_u32 v4, v1, 16, 1
	v_lshrrev_b32_e32 v0, 16, v0
	v_add3_u32 v1, v1, v4, s54
	v_and_or_b32 v0, v1, s33, v0
	v_lshlrev_b32_e32 v1, 16, v3
	v_lshlrev_b32_e32 v4, 16, v7
	v_mul_f32_e32 v1, v27, v1
	v_mul_f32_e32 v4, v19, v4
	v_bfe_u32 v5, v1, 16, 1
	v_add3_u32 v1, v1, v5, s54
	v_bfe_u32 v5, v4, 16, 1
	v_lshrrev_b32_e32 v1, 16, v1
	v_add3_u32 v4, v4, v5, s54
	v_and_or_b32 v1, v4, s33, v1
	v_add_u32_e32 v4, 0x1000, v2
	ds_write2_b32 v4, v0, v1 offset0:132 offset1:200
	v_and_b32_e32 v0, 0xffff0000, v3
	v_and_b32_e32 v1, 0xffff0000, v7
	v_mul_f32_e32 v0, v27, v0
	v_mul_f32_e32 v1, v19, v1
	v_bfe_u32 v3, v0, 16, 1
	v_add3_u32 v0, v0, v3, s54
	v_bfe_u32 v3, v1, 16, 1
	v_lshrrev_b32_e32 v0, 16, v0
	v_add3_u32 v1, v1, v3, s54
	s_ashr_i32 s16, s18, 3
	v_and_or_b32 v0, v1, s33, v0
	v_bfe_u32 v22, v25, 4, 2
	v_bfi_b32 v23, -16, s16, v25
	ds_write_b32 v2, v0 offset:5168
	v_mul_lo_u32 v0, v23, s29
	v_lshlrev_b32_e32 v17, 4, v22
	v_add3_u32 v27, 0, v0, v17
	ds_read_b128 v[0:3], v27
	v_lshl_or_b32 v16, s17, 5, v32
	v_mul_u32_u24_e32 v4, 0x110, v16
	v_add3_u32 v28, 0, v4, v17
	ds_read_b128 v[4:7], v28 offset:17408
	ds_read_b128 v[8:11], v27 offset:64
	ds_read_b128 v[12:15], v28 offset:17472
	s_waitcnt lgkmcnt(2)
	v_mfma_f32_16x16x32_bf16 v[4:7], v[0:3], v[4:7], 0
	ds_read_b128 v[18:21], v28 offset:21760
	ds_read_b128 v[34:37], v28 offset:21824
	s_and_b32 s18, s16, -16
	v_lshl_or_b32 v33, v22, 2, s18
	s_waitcnt lgkmcnt(2)
	v_mfma_f32_16x16x32_bf16 v[4:7], v[8:11], v[12:15], v[4:7]
	ds_read_b128 v[12:15], v27 offset:128
	v_cmp_le_i32_e32 vcc, v16, v33
	s_waitcnt lgkmcnt(2)
	v_mfma_f32_16x16x32_bf16 v[0:3], v[0:3], v[18:21], 0
	s_waitcnt lgkmcnt(1)
	v_mfma_f32_16x16x32_bf16 v[0:3], v[8:11], v[34:37], v[0:3]
	ds_read_b128 v[8:11], v28 offset:17536
	ds_read_b128 v[18:21], v27 offset:192
	ds_read_b128 v[34:37], v28 offset:17600
	s_waitcnt lgkmcnt(2)
	v_mfma_f32_16x16x32_bf16 v[4:7], v[12:15], v[8:11], v[4:7]
	ds_read_b128 v[8:11], v28 offset:21888
	ds_read_b128 v[38:41], v28 offset:21952
	v_lshrrev_b32_e32 v28, 4, v25
	v_bfe_u32 v25, v25, 3, 1
	s_waitcnt lgkmcnt(1)
	v_mfma_f32_16x16x32_bf16 v[0:3], v[12:15], v[8:11], v[0:3]
	v_or_b32_e32 v8, 16, v16
	v_lshlrev_b32_e32 v10, 1, v16
	v_mfma_f32_16x16x32_bf16 v[4:7], v[18:21], v[34:37], v[4:7]
	v_or_b32_e32 v34, 48, v32
	v_lshrrev_b32_e32 v54, 3, v34
	s_waitcnt lgkmcnt(0)
	v_mfma_f32_16x16x32_bf16 v[0:3], v[18:21], v[38:41], v[0:3]
	v_or_b32_e32 v18, 32, v32
	s_nop 2
	v_cndmask_b32_e32 v4, 0, v4, vcc
	v_bfe_u32 v9, v4, 16, 1
	v_add3_u32 v4, v4, v9, s54
	v_mul_lo_u32 v9, v33, s85
	v_cmp_le_i32_e32 vcc, v8, v33
	v_add3_u32 v9, 0, v9, v10
	ds_write_b16_d16_hi v9, v4 offset:34816
	v_cndmask_b32_e32 v0, 0, v0, vcc
	v_bfe_u32 v4, v0, 16, 1
	v_add3_u32 v0, v0, v4, s54
	ds_write_b16_d16_hi v9, v0 offset:34848
	v_or_b32_e32 v0, 1, v33
	v_cmp_le_i32_e32 vcc, v16, v0
	v_lshrrev_b32_e32 v51, 3, v18
	v_bitop3_b32 v18, v51, v28, 3 bitop3:0x78
	v_cndmask_b32_e32 v4, 0, v5, vcc
	v_cmp_le_i32_e32 vcc, v8, v0
	v_bfe_u32 v5, v4, 16, 1
	v_add3_u32 v4, v4, v5, s54
	v_cndmask_b32_e32 v0, 0, v1, vcc
	v_bfe_u32 v1, v0, 16, 1
	v_add3_u32 v0, v0, v1, s54
	ds_write_b16_d16_hi v9, v0 offset:34992
	v_or_b32_e32 v0, 2, v33
	v_cmp_le_i32_e32 vcc, v16, v0
	ds_write_b16_d16_hi v9, v4 offset:34960
	v_lshlrev_b32_e32 v52, 4, v18
	v_cndmask_b32_e32 v1, 0, v6, vcc
	v_bfe_u32 v4, v1, 16, 1
	v_cmp_le_i32_e32 vcc, v8, v0
	v_add3_u32 v1, v1, v4, s54
	ds_write_b16_d16_hi v9, v1 offset:35104
	v_cndmask_b32_e32 v0, 0, v2, vcc
	v_bfe_u32 v1, v0, 16, 1
	v_add3_u32 v0, v0, v1, s54
	ds_write_b16_d16_hi v9, v0 offset:35136
	v_or_b32_e32 v0, 3, v33
	v_cmp_le_i32_e32 vcc, v16, v0
	v_or_b32_e32 v16, s19, v32
	v_mad_u32_u24 v29, v16, s29, 0
	v_cndmask_b32_e32 v1, 0, v7, vcc
	v_bfe_u32 v2, v1, 16, 1
	v_cmp_le_i32_e32 vcc, v8, v0
	v_add3_u32 v1, v1, v2, s54
	ds_write_b16_d16_hi v9, v1 offset:35248
	v_cndmask_b32_e32 v0, 0, v3, vcc
	v_bfe_u32 v1, v0, 16, 1
	v_add3_u32 v0, v0, v1, s54
	v_or_b32_e32 v8, 16, v32
	ds_write_b16_d16_hi v9, v0 offset:35280
	s_waitcnt lgkmcnt(0)
	s_barrier
	ds_read_b128 v[0:3], v27
	v_lshrrev_b32_e32 v48, 3, v8
	v_bitop3_b32 v4, v25, v28, 3 bitop3:0x78
	v_bitop3_b32 v8, v48, v28, 3 bitop3:0x78
	v_bitop3_b32 v28, v54, v28, 3 bitop3:0x78
	v_lshlrev_b32_e32 v46, 4, v4
	v_add_u32_e32 v47, 0x1100, v29
	v_lshlrev_b32_e32 v49, 4, v8
	v_add_u32_e32 v50, 0x2200, v29
	v_add_u32_e32 v53, 0x3300, v29
	v_lshlrev_b32_e32 v28, 4, v28
	v_add_u32_e32 v4, v29, v46
	v_add_u32_e32 v8, v47, v49
	v_add_u32_e32 v18, v50, v52
	v_add_u32_e32 v34, v53, v28
	ds_read_b128 v[4:7], v4 offset:62464
	ds_read_b128 v[8:11], v8 offset:62464
	ds_read_b128 v[12:15], v27 offset:64
	ds_read_b128 v[18:21], v18 offset:62464
	ds_read_b128 v[34:37], v34 offset:62464
	s_waitcnt lgkmcnt(4)
	v_mfma_f32_16x16x32_bf16 v[4:7], v[0:3], v[4:7], 0
	v_bitop3_b32 v38, v48, v22, 4 bitop3:0x1e
	v_lshlrev_b32_e32 v56, 4, v38
	v_add_u32_e32 v38, v47, v56
	s_waitcnt lgkmcnt(3)
	v_mfma_f32_16x16x32_bf16 v[8:11], v[0:3], v[8:11], 0
	ds_read_b128 v[38:41], v38 offset:62464
	v_cmp_eq_u32_e32 vcc, 0, v32
	s_waitcnt lgkmcnt(2)
	v_mfma_f32_16x16x32_bf16 v[18:21], v[0:3], v[18:21], 0
	s_waitcnt lgkmcnt(1)
	v_mfma_f32_16x16x32_bf16 v[0:3], v[0:3], v[34:37], 0
	v_bitop3_b32 v34, v22, v25, 4 bitop3:0x36
	v_lshlrev_b32_e32 v55, 4, v34
	v_add_u32_e32 v34, v29, v55
	ds_read_b128 v[34:37], v34 offset:62464
	s_waitcnt lgkmcnt(1)
	v_mfma_f32_16x16x32_bf16 v[8:11], v[12:15], v[38:41], v[8:11]
	v_bitop3_b32 v38, v54, v22, 4 bitop3:0x1e
	v_lshlrev_b32_e32 v58, 4, v38
	v_add_u32_e32 v38, v53, v58
	s_waitcnt lgkmcnt(0)
	v_mfma_f32_16x16x32_bf16 v[4:7], v[12:15], v[34:37], v[4:7]
	v_bitop3_b32 v34, v51, v22, 4 bitop3:0x1e
	v_lshlrev_b32_e32 v57, 4, v34
	v_add_u32_e32 v34, v50, v57
	ds_read_b128 v[34:37], v34 offset:62464
	ds_read_b128 v[38:41], v38 offset:62464
	s_waitcnt lgkmcnt(1)
	v_mfma_f32_16x16x32_bf16 v[18:21], v[12:15], v[34:37], v[18:21]
	ds_read_b128 v[34:37], v27 offset:128
	s_waitcnt lgkmcnt(1)
	v_mfma_f32_16x16x32_bf16 v[0:3], v[12:15], v[38:41], v[0:3]
	v_bitop3_b32 v12, v22, v25, 8 bitop3:0x36
	v_lshl_add_u32 v12, v12, 4, v29
	ds_read_b128 v[12:15], v12 offset:62464
	v_bitop3_b32 v38, v48, v22, 8 bitop3:0x1e
	s_waitcnt lgkmcnt(0)
	v_mfma_f32_16x16x32_bf16 v[4:7], v[34:37], v[12:15], v[4:7]
	v_bitop3_b32 v12, v51, v22, 8 bitop3:0x1e
	v_lshl_add_u32 v38, v38, 4, v47
	v_lshl_add_u32 v12, v12, 4, v50
	ds_read_b128 v[38:41], v38 offset:62464
	ds_read_b128 v[42:45], v27 offset:192
	ds_read_b128 v[12:15], v12 offset:62464
	v_bitop3_b32 v27, v54, v22, 8 bitop3:0x1e
	v_lshl_add_u32 v27, v27, 4, v53
	s_waitcnt lgkmcnt(2)
	v_mfma_f32_16x16x32_bf16 v[8:11], v[34:37], v[38:41], v[8:11]
	ds_read_b128 v[38:41], v27 offset:62464
	s_waitcnt lgkmcnt(1)
	v_mfma_f32_16x16x32_bf16 v[12:15], v[34:37], v[12:15], v[18:21]
	s_nop 2
	v_bitop3_b32 v18, v22, v25, 12 bitop3:0x36
	v_lshl_add_u32 v18, v18, 4, v29
	ds_read_b128 v[18:21], v18 offset:62464
	v_bitop3_b32 v25, v48, v22, 12 bitop3:0x1e
	v_lshl_add_u32 v25, v25, 4, v47
	s_waitcnt lgkmcnt(1)
	v_mfma_f32_16x16x32_bf16 v[0:3], v[34:37], v[38:41], v[0:3]
	ds_read_b128 v[34:37], v25 offset:62464
	s_waitcnt lgkmcnt(1)
	v_mfma_f32_16x16x32_bf16 v[4:7], v[42:45], v[18:21], v[4:7]
	v_bitop3_b32 v18, v51, v22, 12 bitop3:0x1e
	v_lshl_add_u32 v18, v18, 4, v50
	ds_read_b128 v[18:21], v18 offset:62464
	v_bitop3_b32 v22, v54, v22, 12 bitop3:0x1e
	v_lshl_add_u32 v22, v22, 4, v53
	s_waitcnt lgkmcnt(1)
	v_mfma_f32_16x16x32_bf16 v[8:11], v[42:45], v[34:37], v[8:11]
	ds_read_b128 v[34:37], v22 offset:62464
	s_waitcnt lgkmcnt(1)
	v_mfma_f32_16x16x32_bf16 v[12:15], v[42:45], v[18:21], v[12:15]
	v_mul_lo_u32 v18, v23, s85
	v_add3_u32 v22, 0, v18, v17
	ds_read_b128 v[18:21], v22 offset:34816
	v_mul_u32_u24_e32 v23, 0x90, v16
	v_add3_u32 v25, 0, v46, v23
	s_waitcnt lgkmcnt(1)
	v_mfma_f32_16x16x32_bf16 v[0:3], v[42:45], v[34:37], v[0:3]
	ds_read_b128 v[34:37], v25 offset:44032
	v_mad_u32_u24 v25, v16, s85, v198
	v_add3_u32 v27, 0, v49, v25
	ds_read_b128 v[38:41], v27 offset:44032
	ds_read_b128 v[42:45], v22 offset:34880
	v_mad_u32_u24 v22, v16, s85, v199
	v_add3_u32 v27, 0, v52, v22
	s_waitcnt lgkmcnt(2)
	v_mfma_f32_16x16x32_bf16 v[4:7], v[18:21], v[34:37], v[4:7]
	ds_read_b128 v[34:37], v27 offset:44032
	v_mad_u32_u24 v27, v16, s85, v200
	v_add3_u32 v28, 0, v28, v27
	s_waitcnt lgkmcnt(2)
	v_mfma_f32_16x16x32_bf16 v[8:11], v[18:21], v[38:41], v[8:11]
	ds_read_b128 v[38:41], v28 offset:44032
	s_waitcnt lgkmcnt(1)
	v_mfma_f32_16x16x32_bf16 v[34:37], v[18:21], v[34:37], v[12:15]
	s_nop 2
	v_add3_u32 v12, 0, v55, v23
	ds_read_b128 v[12:15], v12 offset:44032
	s_waitcnt lgkmcnt(1)
	v_mfma_f32_16x16x32_bf16 v[0:3], v[18:21], v[38:41], v[0:3]
	v_add3_u32 v18, 0, v56, v25
	ds_read_b128 v[18:21], v18 offset:44032
	s_waitcnt lgkmcnt(1)
	v_mfma_f32_16x16x32_bf16 v[12:15], v[42:45], v[12:15], v[4:7]
	s_nop 2
	v_add3_u32 v4, 0, v57, v22
	ds_read_b128 v[4:7], v4 offset:44032
	s_waitcnt lgkmcnt(1)
	v_mfma_f32_16x16x32_bf16 v[8:11], v[42:45], v[18:21], v[8:11]
	v_add3_u32 v18, 0, v58, v27
	ds_read_b128 v[18:21], v18 offset:44032
	s_waitcnt lgkmcnt(0)
	v_mfma_f32_16x16x32_bf16 v[0:3], v[42:45], v[18:21], v[0:3]
	s_nop 3
	v_mul_f32_e64 v18, v10, v10
	v_mul_f32_e64 v19, v11, v11
	v_pk_mul_f32 v[20:21], v[8:9], v[8:9]
	v_mfma_f32_16x16x32_bf16 v[4:7], v[42:45], v[4:7], v[34:37]
	v_mul_f32_e64 v22, v2, v2
	v_mul_f32_e64 v23, v3, v3
	v_pk_mul_f32 v[28:29], v[0:1], v[0:1]
	v_pk_fma_f32 v[18:19], v[14:15], v[14:15], v[18:19]
	v_pk_fma_f32 v[20:21], v[12:13], v[12:13], v[20:21]
	s_nop 2
	v_pk_fma_f32 v[22:23], v[6:7], v[6:7], v[22:23]
	v_pk_fma_f32 v[28:29], v[4:5], v[4:5], v[28:29]
	v_pk_add_f32 v[22:23], v[18:19], v[22:23]
	v_pk_add_f32 v[18:19], v[20:21], v[28:29]
	s_nop 0
	v_mov_b32_dpp v28, v22 quad_perm:[1,0,3,2] row_mask:0xf bank_mask:0xf bound_ctrl:1
	v_mov_b32_dpp v20, v18 quad_perm:[1,0,3,2] row_mask:0xf bank_mask:0xf bound_ctrl:1
	v_mov_b32_dpp v21, v19 quad_perm:[1,0,3,2] row_mask:0xf bank_mask:0xf bound_ctrl:1
	v_mov_b32_dpp v29, v23 quad_perm:[1,0,3,2] row_mask:0xf bank_mask:0xf bound_ctrl:1
	v_pk_add_f32 v[18:19], v[18:19], v[20:21]
	v_pk_add_f32 v[22:23], v[22:23], v[28:29]
	s_nop 0
	v_mov_b32_dpp v20, v18 quad_perm:[2,3,0,1] row_mask:0xf bank_mask:0xf bound_ctrl:1
	v_mov_b32_dpp v21, v19 quad_perm:[2,3,0,1] row_mask:0xf bank_mask:0xf bound_ctrl:1
	v_mov_b32_dpp v28, v22 quad_perm:[2,3,0,1] row_mask:0xf bank_mask:0xf bound_ctrl:1
	v_mov_b32_dpp v29, v23 quad_perm:[2,3,0,1] row_mask:0xf bank_mask:0xf bound_ctrl:1
	v_pk_add_f32 v[18:19], v[18:19], v[20:21]
	v_pk_add_f32 v[22:23], v[22:23], v[28:29]
	s_nop 0
	v_mov_b32_dpp v20, v18 row_half_mirror row_mask:0xf bank_mask:0xf bound_ctrl:1
	v_mov_b32_dpp v21, v19 row_half_mirror row_mask:0xf bank_mask:0xf bound_ctrl:1
	v_mov_b32_dpp v28, v22 row_half_mirror row_mask:0xf bank_mask:0xf bound_ctrl:1
	v_mov_b32_dpp v29, v23 row_half_mirror row_mask:0xf bank_mask:0xf bound_ctrl:1
	v_pk_add_f32 v[18:19], v[18:19], v[20:21]
	v_pk_add_f32 v[22:23], v[22:23], v[28:29]
	s_nop 0
	v_mov_b32_dpp v20, v18 row_mirror row_mask:0xf bank_mask:0xf bound_ctrl:1
	v_mov_b32_dpp v21, v19 row_mirror row_mask:0xf bank_mask:0xf bound_ctrl:1
	v_mov_b32_dpp v28, v22 row_mirror row_mask:0xf bank_mask:0xf bound_ctrl:1
	v_mov_b32_dpp v29, v23 row_mirror row_mask:0xf bank_mask:0xf bound_ctrl:1
	s_and_saveexec_b64 s[16:17], vcc
	s_cbranch_execz .LBB0_1031
	s_lshl_b32 s19, s19, 2
	s_add_i32 s19, s19, 0
	s_lshl_b32 s18, s18, 2
	s_add_i32 s19, s19, s18
	v_add_u32_e32 v17, s19, v17
	v_add_u32_e32 v17, 0x1fe00, v17
	v_pk_add_f32 v[18:19], v[18:19], v[20:21]
	v_pk_add_f32 v[20:21], v[22:23], v[28:29]
	ds_write_b128 v17, v[18:21]
	s_branch .LBB0_1031
